# adds the P2 and final residual epilogues' base-tile prefetch (three groups ahead) to the placement-compensated combination
# baseline (speedup 1.0000x reference)
.LBB0_611:
	s_mov_b64 s[60:61], 0x80
	s_lshl_b32 s4, s4, 5
	s_add_i32 m0, s11, 0x18000
	v_lshl_add_u64 v[8:9], v[8:9], 0, s[60:61]
	s_lshl_b32 s55, s5, 6
	s_lshl_b32 s1, s5, 13
	s_and_b32 s7, s4, 0x60
	s_waitcnt vmcnt(2)
	s_barrier
	global_load_lds_dwordx4 v[8:9], off
	v_lshl_add_u64 v[6:7], v[6:7], 0, s[60:61]
	s_add_i32 m0, s11, 0x1a000
	s_add_i32 s56, s11, 0x8000
	s_add_i32 s57, s11, 0xa000
	global_load_lds_dwordx4 v[6:7], off
	v_lshl_add_u64 v[2:3], v[2:3], 0, s[60:61]
	s_mov_b32 m0, s56
	s_add_u32 s4, s92, 0x40080
	global_load_lds_dwordx4 v[2:3], off
	v_lshl_add_u64 v[2:3], v[4:5], 0, s[60:61]
	s_mov_b32 m0, s57
	s_addc_u32 s5, s93, 0
	global_load_lds_dwordx4 v[2:3], off
	s_add_i32 m0, s11, 0x1c000
	v_lshl_add_u64 v[2:3], s[4:5], 0, v[148:149]
	global_load_lds_dwordx4 v[2:3], off
	v_lshl_add_u64 v[2:3], s[4:5], 0, v[152:153]
	s_add_i32 m0, s11, 0x1e000
	s_movk_i32 s4, 0x3c0
	global_load_lds_dwordx4 v[2:3], off
	v_lshlrev_b32_e32 v2, 6, v169
	v_lshlrev_b32_e32 v3, 2, v169
	v_and_or_b32 v2, v2, s4, v201
	v_and_b32_e32 v3, 32, v3
	v_bitop3_b32 v2, v2, s1, v3 bitop3:0xde
	v_lshlrev_b32_e32 v3, 8, v0
	v_and_b32_e32 v3, 0x18000, v3
	v_lshlrev_b32_e32 v4, 11, v1
	v_or3_b32 v3, v173, v3, v4
	v_add_u32_e32 v132, v3, v179
	v_lshlrev_b32_e32 v3, 4, v200
	s_waitcnt vmcnt(6)
	s_cmpk_lt_u32 s6, 0x100
	v_and_b32_e32 v3, 0x38000, v3
	v_lshl_or_b32 v131, s7, 7, v254
	s_cselect_b64 s[68:69], -1, 0
	v_or3_b32 v3, v173, v3, v4
	s_add_i32 s66, 0, 0x10000
	s_add_i32 s67, 0, 0x14000
	s_movk_i32 s78, 0xf400
	s_movk_i32 s80, 0xf500
	s_ashr_i32 s64, s3, 31
	s_ashr_i32 s65, s2, 31
	v_or_b32_e32 v145, s7, v154
	v_mov_b32_e32 v133, v149
	v_add_u32_e32 v134, v3, v179
	v_mov_b32_e32 v135, v149
	v_mov_b64_e32 v[136:137], 0x37f
	s_mov_b64 s[70:71], 0x100
	v_add_u32_e32 v155, s66, v131
	v_add_u32_e32 v157, s67, v131
	v_add_u32_e32 v159, 0, v2
	v_mov_b32_e32 v161, 0x358637bd
	s_mov_b32 s85, 0x800000
	s_movk_i32 s94, 0xe40
	s_movk_i32 s95, 0xc00
	s_movk_i32 s96, 0xd20
	s_movk_i32 s97, 0x5ff
	s_mov_b32 s79, -1
	s_mov_b32 s81, -1
	v_mov_b32_e32 v163, 0x1fcf
	s_barrier
	s_branch .LBB0_614
	s_nop 0
	s_nop 0
	s_nop 0
	s_nop 0
	s_nop 0
	s_nop 0
	s_nop 0
	s_nop 0

.LBB0_1878:
	s_sub_i32 s24, s53, 21
	s_cmp_lt_u32 s53, 53
	s_cselect_b32 s28, s24, s53
	s_cbranch_execz .LBB0_1873
	s_branch .LBB0_1874
	s_nop 0
	s_nop 0
	s_nop 0
	s_nop 0
	s_nop 0
	s_nop 0
